# gated-delta chunk prep: the forward-substitution waves of the two half-workgroups now sit on four SIMDs instead of two (roles of waves 4-7 rotated by two)
# speedup vs baseline: 1.0312x; 1.0124x over previous
.LBB0_1339:
	v_readlane_b32 s0, v255, 12
	v_readlane_b32 s1, v255, 13
	s_cmp_lt_i32 s0, 6
	s_cselect_b64 s[0:1], -1, 0
	s_and_b64 s[50:51], s[0:1], s[2:3]
	s_andn2_b64 vcc, exec, s[50:51]
	s_cbranch_vccnz .LBB0_1526
	s_abs_i32 s0, s73
	s_waitcnt vmcnt(0)
	v_cvt_f32_u32_e32 v1, s0
	s_and_b32 s37, s87, 0xffffffc0
	v_mbcnt_lo_u32_b32 v0, -1, 0
	v_mbcnt_hi_u32_b32 v0, -1, v0
	s_sub_i32 s4, 0, s0
	v_add_u32_e32 v0, s37, v0
	s_add_i32 s1, s73, 0x1ff
	v_rcp_iflag_f32_e32 v0, v1
	s_xor_b32 s3, s1, s73
	s_abs_i32 s1, s1
	s_ashr_i32 s3, s3, 31
	v_mul_f32_e32 v0, 0x4f7ffffe, v0
	v_cvt_u32_f32_e32 v0, v0
	s_mov_b32 s53, 0
	s_mov_b32 s2, 0
	v_readfirstlane_b32 s5, v0
	s_mul_i32 s4, s4, s5
	s_mul_hi_u32 s4, s5, s4
	s_add_i32 s5, s5, s4
	s_mul_hi_u32 s4, s1, s5
	s_mul_i32 s5, s4, s0
	s_sub_i32 s1, s1, s5
	s_add_i32 s5, s4, 1
	s_sub_i32 s6, s1, s0
	s_cmp_ge_u32 s1, s0
	s_cselect_b32 s4, s5, s4
	s_cselect_b32 s1, s6, s1
	s_add_i32 s5, s4, 1
	s_cmp_ge_u32 s1, s0
	s_cselect_b32 s0, s5, s4
	s_xor_b32 s0, s0, s3
	s_sub_i32 s0, s0, s3
	s_lshl_b32 s0, s0, 1
	s_mul_i32 s39, s0, s33
	s_add_i32 s0, s39, s0
	s_min_i32 s44, s0, 0x400
	s_cmp_ge_i32 s39, s44
	s_cbranch_scc1 .LBB0_1526
	s_ashr_i32 s3, s2, 31
	v_readlane_b32 s0, v255, 4
	v_readlane_b32 s1, v255, 5
	s_add_u32 s4, s0, s2
	s_addc_u32 s5, s1, s3
	s_lshr_b32 s45, s87, 8
	s_mul_i32 s0, s45, 0x11000
	s_add_i32 s46, s0, 0
	s_bfe_u32 s0, s87, 0x20006
	s_lshl_b32 s1, s45, 1
	s_xor_b32 s0, s0, s1
	s_add_i32 s47, s46, 0x8000
	s_add_i32 s49, s46, 0x10800
	s_lshl_b32 s65, s0, 4
	s_cmp_eq_u32 s0, 0
	s_cselect_b64 s[54:55], -1, 0
	s_cmp_lg_u32 s0, 0
	s_cselect_b64 s[56:57], -1, 0
	s_cmp_lt_u32 s0, 2
	s_cselect_b64 s[58:59], -1, 0
	s_lshl_b32 s0, s0, 8
	s_add_i32 s70, s46, s0
	s_lshl_b64 s[0:1], s[2:3], 3
	v_readlane_b32 s2, v255, 2
	v_readlane_b32 s3, v255, 3
	s_add_u32 s60, s2, s0
	s_addc_u32 s61, s3, s1
	s_add_u32 s71, s4, 0x38000000
	s_addc_u32 s72, s5, 0
	s_add_u32 s62, s4, 0x3c300000
	s_addc_u32 s63, s5, 0
	s_add_u32 s74, s4, 0x58800000
	s_addc_u32 s76, s5, 0
	s_add_u32 s77, s4, 0x55d00000
	s_addc_u32 s78, s5, 0
	s_add_u32 s79, s4, 0x56e00000
	s_addc_u32 s80, s5, 0
	s_add_u32 s81, s4, 0x57f00000
	s_addc_u32 s82, s5, 0
	s_add_u32 s83, s4, 0x54c00000
	s_addc_u32 s84, s5, 0
	s_add_u32 s85, s4, 0x52a00000
	v_readlane_b32 s0, v255, 9
	s_addc_u32 s86, s5, 0
	s_lshl_b32 s0, s0, 8
	v_mbcnt_lo_u32_b32 v0, -1, 0
	s_add_i32 s87, s0, 0
	v_mbcnt_hi_u32_b32 v132, -1, v0
	v_bfrev_b32_e32 v0, 0.5
	s_add_i32 s87, s87, 0x22000
	s_mov_b32 s95, -1
	v_mov_b32_e32 v109, 0
	s_movk_i32 s88, 0x1000
	s_movk_i32 s89, 0x1800
	s_add_i32 s90, 0, 0x22800
	s_mov_b32 s91, 0x800000
	v_lshl_or_b32 v133, v132, 2, v0
	s_mov_b32 s64, 0x358637bd
	s_movk_i32 s92, 0x110
	s_movk_i32 s93, 0x2000
	s_movk_i32 s94, 0x3000
	v_mov_b32_e32 v134, 0x41b17218
	v_readlane_b32 s1, v255, 10
	s_branch .LBB0_1343
